# P2 queue: next index fetched one tile early and consumed with a counted vmcnt(8) (atomic is older than the unit's 8+ trailing stores), so neither the atomic nor the store acks are waited on
# baseline (speedup 1.0000x reference)
.Lq_pre:
	s_or_b64 exec, exec, s[98:99]
	s_waitcnt vmcnt(0)
	s_branch .LBB0_445

.LBB0_445:
	s_and_saveexec_b64 s[14:15], s[90:91]
	s_cbranch_execz .LBB0_449
	s_mov_b64 s[18:19], exec
	v_mbcnt_lo_u32_b32 v0, s18, 0
	v_mbcnt_hi_u32_b32 v0, s19, v0
	v_cmp_eq_u32_e32 vcc, 0, v0
	s_and_saveexec_b64 s[16:17], vcc
	s_cbranch_execz .LBB0_448
	s_waitcnt vmcnt(8)
	v_mov_b32_e32 v2, v199
